# hand-written rmsnorm+adaLN row kernels for the P2 tail filler and the group-0 input norm (two rows in flight, loads batched, DPP reduction)
# speedup vs baseline: 1.0035x; 1.0035x over previous
; DEV int tidx() { return tidx_full() & 255; }
; #define VBID ((int)blockIdx.x * 2 + vhalf())
; DEV void phase_norm_adaln(const float* __restrict__ X, const float* __restrict__ gvec, const float* __restrict__ mod,
;                           int bg0, int L, int sh_off, int sc_off, u16* __restrict__ H) {
;   const int tid = tidx();
;   const int wave = tid >> 6, lane = tid & 63;
;   constexpr int RB = 4;
;   const int stride = NVB * 4;
;   for (int row0 = VBID * 4 + wave; row0 < NTOK; row0 += stride * RB) {
;     float4 v[RB][4];
;     float ss[RB];
; #pragma unroll
;     for (int j = 0; j < RB; ++j) {
;       const int row = row0 + j * stride;
;       const float* x = X + (long)(row < NTOK ? row : row0) * D;
; #pragma unroll
;       for (int i = 0; i < 4; ++i) v[j][i] = *(const float4*)(x + lane * 4 + 256 * i);
;     }
; #pragma unroll
;     for (int j = 0; j < RB; ++j) {
;       float t = 0.f;
; #pragma unroll
;       for (int i = 0; i < 4; ++i) t += v[j][i].x * v[j][i].x + v[j][i].y * v[j][i].y + v[j][i].z * v[j][i].z + v[j][i].w * v[j][i].w;
;       ss[j] = wave_sum(t);
;     }
; #pragma unroll
;     for (int j = 0; j < RB; ++j) {
;       const int row = row0 + j * stride;
;       if (row < NTOK) {
;         const float rstd = rsqrtf(ss[j] * (1.f / 1024.f) + EPSF);
;         const float* mrow = mod + (long)(bg0 + row / L) * DIN;
; #pragma unroll
;         for (int i = 0; i < 4; ++i) {
;           const int k = lane * 4 + 256 * i;
;           const float4 g = *(const float4*)(gvec + k);
;           const float4 sc = *(const float4*)(mrow + sc_off + k);
;           const float4 sh = *(const float4*)(mrow + sh_off + k);
;           const float o0 = v[j][i].x * rstd * g.x * (1.f + sc.x) + sh.x;
;           const float o1 = v[j][i].y * rstd * g.y * (1.f + sc.y) + sh.y;
;           const float o2 = v[j][i].z * rstd * g.z * (1.f + sc.z) + sh.z;
;           const float o3 = v[j][i].w * rstd * g.w * (1.f + sc.w) + sh.w;
;           *(uint2*)(H + (long)row * D + k) = make_uint2(pack2(o0, o1), pack2(o2, o3));
;         }
;       }
;     }
;   }
; }
.LBB0_195:
	v_readfirstlane_b32 s12, v202
	s_lshl_b32 s13, s80, 3
	s_lshr_b32 s12, s12, 6
	s_add_u32 s12, s12, s13
	v_mov_b32_e32 v127, 0x358637bd
	v_and_b32_e32 v124, 63, v202
	v_lshlrev_b32_e32 v125, 3, v124
	v_lshlrev_b32_e32 v124, 4, v124
	global_load_dwordx4 v[96:99], v124, s[64:65]
	global_load_dwordx4 v[100:103], v124, s[64:65] offset:1024
	global_load_dwordx4 v[104:107], v124, s[64:65] offset:2048
	global_load_dwordx4 v[108:111], v124, s[64:65] offset:3072
	s_lshl_b32 s13, s12, 11
	s_add_u32 s14, s78, s13
	s_addc_u32 s15, s79, 0
	s_lshl_b32 s13, s12, 12
	s_add_u32 s0, s52, s13
	s_addc_u32 s1, s53, 0
	s_lshr_b32 s13, s12, 12
	s_mul_i32 s13, s13, 0x6000
	s_add_u32 s16, s86, s13
	s_addc_u32 s17, s87, 0
	s_add_u32 s4, s16, 0x1000
	s_addc_u32 s5, s17, 0
	s_add_u32 s8, s16, 0x0
	s_addc_u32 s9, s17, 0
	global_load_dwordx4 v[0:3], v124, s[0:1]
	global_load_dwordx4 v[4:7], v124, s[0:1] offset:1024
	global_load_dwordx4 v[8:11], v124, s[0:1] offset:2048
	global_load_dwordx4 v[12:15], v124, s[0:1] offset:3072
	global_load_dwordx4 v[32:35], v124, s[4:5]
	global_load_dwordx4 v[36:39], v124, s[4:5] offset:1024
	global_load_dwordx4 v[40:43], v124, s[4:5] offset:2048
	global_load_dwordx4 v[44:47], v124, s[4:5] offset:3072
	global_load_dwordx4 v[48:51], v124, s[8:9]
	global_load_dwordx4 v[52:55], v124, s[8:9] offset:1024
	global_load_dwordx4 v[56:59], v124, s[8:9] offset:2048
	global_load_dwordx4 v[60:63], v124, s[8:9] offset:3072
	s_add_u32 s12, s12, 0x800
	s_lshl_b32 s13, s12, 12
	s_add_u32 s0, s52, s13
	s_addc_u32 s1, s53, 0
	s_lshr_b32 s13, s12, 12
	s_mul_i32 s13, s13, 0x6000
	s_add_u32 s16, s86, s13
	s_addc_u32 s17, s87, 0
	s_add_u32 s4, s16, 0x1000
	s_addc_u32 s5, s17, 0
	s_add_u32 s8, s16, 0x0
	s_addc_u32 s9, s17, 0
	global_load_dwordx4 v[16:19], v124, s[0:1]
	global_load_dwordx4 v[20:23], v124, s[0:1] offset:1024
	global_load_dwordx4 v[24:27], v124, s[0:1] offset:2048
	global_load_dwordx4 v[28:31], v124, s[0:1] offset:3072
	global_load_dwordx4 v[64:67], v124, s[4:5]
	global_load_dwordx4 v[68:71], v124, s[4:5] offset:1024
	global_load_dwordx4 v[72:75], v124, s[4:5] offset:2048
	global_load_dwordx4 v[76:79], v124, s[4:5] offset:3072
	global_load_dwordx4 v[80:83], v124, s[8:9]
	global_load_dwordx4 v[84:87], v124, s[8:9] offset:1024
	global_load_dwordx4 v[88:91], v124, s[8:9] offset:2048
	global_load_dwordx4 v[92:95], v124, s[8:9] offset:3072
	s_add_u32 s12, s12, 0x800
	s_mov_b32 s18, 0
.Lnorm1_loop:
	s_waitcnt vmcnt(12)
	v_mul_f32_e32 v121, v0, v0
	v_fmac_f32_e32 v121, v1, v1
	v_fmac_f32_e32 v121, v2, v2
	v_fmac_f32_e32 v121, v3, v3
	v_fmac_f32_e32 v121, v4, v4
	v_fmac_f32_e32 v121, v5, v5
	v_fmac_f32_e32 v121, v6, v6
	v_fmac_f32_e32 v121, v7, v7
	v_fmac_f32_e32 v121, v8, v8
	v_fmac_f32_e32 v121, v9, v9
	v_fmac_f32_e32 v121, v10, v10
	v_fmac_f32_e32 v121, v11, v11
	v_fmac_f32_e32 v121, v12, v12
	v_fmac_f32_e32 v121, v13, v13
	v_fmac_f32_e32 v121, v14, v14
	v_fmac_f32_e32 v121, v15, v15
	s_nop 1
	v_add_f32_dpp v121, v121, v121 quad_perm:[1,0,3,2] row_mask:0xf bank_mask:0xf
	s_nop 1
	v_add_f32_dpp v121, v121, v121 quad_perm:[2,3,0,1] row_mask:0xf bank_mask:0xf
	s_nop 1
	v_add_f32_dpp v121, v121, v121 row_half_mirror row_mask:0xf bank_mask:0xf
	s_nop 1
	v_add_f32_dpp v121, v121, v121 row_mirror row_mask:0xf bank_mask:0xf
	s_nop 1
	v_add_f32_dpp v121, v121, v121 row_bcast:15 row_mask:0xa bank_mask:0xf
	s_nop 1
	v_add_f32_dpp v121, v121, v121 row_bcast:31 row_mask:0xc bank_mask:0xf
	s_nop 1
	v_readlane_b32 s13, v121, 63
	v_mov_b32_e32 v122, 0x3a800000
	s_nop 1
	v_fma_f32 v126, s13, v122, v127
	v_cmp_gt_f32_e32 vcc, 0x800000, v126
	v_mul_f32_e32 v123, 0x4b800000, v126
	v_cndmask_b32_e32 v126, v126, v123, vcc
	v_rsq_f32_e32 v126, v126
	s_nop 0
	v_mul_f32_e32 v123, 0x45800000, v126
	v_cndmask_b32_e32 v126, v126, v123, vcc
	v_mul_f32_e32 v0, v0, v126
	v_mul_f32_e32 v0, v96, v0
	v_add_f32_e32 v32, 1.0, v32
	v_fma_f32 v0, v0, v32, v48
	v_mul_f32_e32 v1, v1, v126
	v_mul_f32_e32 v1, v97, v1
	v_add_f32_e32 v33, 1.0, v33
	v_fma_f32 v1, v1, v33, v49
	v_mul_f32_e32 v2, v2, v126
	v_mul_f32_e32 v2, v98, v2
	v_add_f32_e32 v34, 1.0, v34
	v_fma_f32 v2, v2, v34, v50
	v_mul_f32_e32 v3, v3, v126
	v_mul_f32_e32 v3, v99, v3
	v_add_f32_e32 v35, 1.0, v35
	v_fma_f32 v3, v3, v35, v51
	v_mul_f32_e32 v4, v4, v126
	v_mul_f32_e32 v4, v100, v4
	v_add_f32_e32 v36, 1.0, v36
	v_fma_f32 v4, v4, v36, v52
	v_mul_f32_e32 v5, v5, v126
	v_mul_f32_e32 v5, v101, v5
	v_add_f32_e32 v37, 1.0, v37
	v_fma_f32 v5, v5, v37, v53
	v_mul_f32_e32 v6, v6, v126
	v_mul_f32_e32 v6, v102, v6
	v_add_f32_e32 v38, 1.0, v38
	v_fma_f32 v6, v6, v38, v54
	v_mul_f32_e32 v7, v7, v126
	v_mul_f32_e32 v7, v103, v7
	v_add_f32_e32 v39, 1.0, v39
	v_fma_f32 v7, v7, v39, v55
	v_mul_f32_e32 v8, v8, v126
	v_mul_f32_e32 v8, v104, v8
	v_add_f32_e32 v40, 1.0, v40
	v_fma_f32 v8, v8, v40, v56
	v_mul_f32_e32 v9, v9, v126
	v_mul_f32_e32 v9, v105, v9
	v_add_f32_e32 v41, 1.0, v41
	v_fma_f32 v9, v9, v41, v57
	v_mul_f32_e32 v10, v10, v126
	v_mul_f32_e32 v10, v106, v10
	v_add_f32_e32 v42, 1.0, v42
	v_fma_f32 v10, v10, v42, v58
	v_mul_f32_e32 v11, v11, v126
	v_mul_f32_e32 v11, v107, v11
	v_add_f32_e32 v43, 1.0, v43
	v_fma_f32 v11, v11, v43, v59
	v_mul_f32_e32 v12, v12, v126
	v_mul_f32_e32 v12, v108, v12
	v_add_f32_e32 v44, 1.0, v44
	v_fma_f32 v12, v12, v44, v60
	v_mul_f32_e32 v13, v13, v126
	v_mul_f32_e32 v13, v109, v13
	v_add_f32_e32 v45, 1.0, v45
	v_fma_f32 v13, v13, v45, v61
	v_mul_f32_e32 v14, v14, v126
	v_mul_f32_e32 v14, v110, v14
	v_add_f32_e32 v46, 1.0, v46
	v_fma_f32 v14, v14, v46, v62
	v_mul_f32_e32 v15, v15, v126
	v_mul_f32_e32 v15, v111, v15
	v_add_f32_e32 v47, 1.0, v47
	v_fma_f32 v15, v15, v47, v63
	v_cvt_pk_bf16_f32 v0, v0, v1
	v_cvt_pk_bf16_f32 v1, v2, v3
	global_store_dwordx2 v125, v[0:1], s[14:15]
	v_cvt_pk_bf16_f32 v4, v4, v5
	v_cvt_pk_bf16_f32 v5, v6, v7
	global_store_dwordx2 v125, v[4:5], s[14:15] offset:512
	v_cvt_pk_bf16_f32 v8, v8, v9
	v_cvt_pk_bf16_f32 v9, v10, v11
	global_store_dwordx2 v125, v[8:9], s[14:15] offset:1024
	v_cvt_pk_bf16_f32 v12, v12, v13
	v_cvt_pk_bf16_f32 v13, v14, v15
	global_store_dwordx2 v125, v[12:13], s[14:15] offset:1536
	s_add_u32 s14, s14, 0x400000
	s_addc_u32 s15, s15, 0
	s_cmp_eq_u32 s18, 7
	s_cbranch_scc1 .Lnorm1_tail
; #define VBID ((int)blockIdx.x * 2 + vhalf())
; DEV void phase_norm_adaln(const float* __restrict__ X, const float* __restrict__ gvec, const float* __restrict__ mod,
;                           int bg0, int L, int sh_off, int sc_off, u16* __restrict__ H) {
;     ...
;   for (int row0 = VBID * 4 + wave; row0 < NTOK; row0 += stride * RB) {
;     float4 v[RB][4];
;     float ss[RB];
; #pragma unroll
;     for (int j = 0; j < RB; ++j) {
;       const int row = row0 + j * stride;
;       const float* x = X + (long)(row < NTOK ? row : row0) * D;
; #pragma unroll
;       for (int i = 0; i < 4; ++i) v[j][i] = *(const float4*)(x + lane * 4 + 256 * i);
;     }
; #pragma unroll
;     for (int j = 0; j < RB; ++j) {
;       float t = 0.f;
; #pragma unroll
;       for (int i = 0; i < 4; ++i) t += v[j][i].x * v[j][i].x + v[j][i].y * v[j][i].y + v[j][i].z * v[j][i].z + v[j][i].w * v[j][i].w;
;       ss[j] = wave_sum(t);
;     }
; #pragma unroll
;     for (int j = 0; j < RB; ++j) {
;       const int row = row0 + j * stride;
;       if (row < NTOK) {
;         const float rstd = rsqrtf(ss[j] * (1.f / 1024.f) + EPSF);
;         const float* mrow = mod + (long)(bg0 + row / L) * DIN;
; #pragma unroll
;         for (int i = 0; i < 4; ++i) {
;           const int k = lane * 4 + 256 * i;
;           const float4 g = *(const float4*)(gvec + k);
;           const float4 sc = *(const float4*)(mrow + sc_off + k);
;           const float4 sh = *(const float4*)(mrow + sh_off + k);
;           const float o0 = v[j][i].x * rstd * g.x * (1.f + sc.x) + sh.x;
;           const float o1 = v[j][i].y * rstd * g.y * (1.f + sc.y) + sh.y;
;           const float o2 = v[j][i].z * rstd * g.z * (1.f + sc.z) + sh.z;
;           const float o3 = v[j][i].w * rstd * g.w * (1.f + sc.w) + sh.w;
;           *(uint2*)(H + (long)row * D + k) = make_uint2(pack2(o0, o1), pack2(o2, o3));
;         }
;       }
;     }
;   }
	s_lshl_b32 s13, s12, 12
	s_add_u32 s0, s52, s13
	s_addc_u32 s1, s53, 0
	s_lshr_b32 s13, s12, 12
	s_mul_i32 s13, s13, 0x6000
	s_add_u32 s16, s86, s13
	s_addc_u32 s17, s87, 0
	s_add_u32 s4, s16, 0x1000
	s_addc_u32 s5, s17, 0
	s_add_u32 s8, s16, 0x0
	s_addc_u32 s9, s17, 0
	global_load_dwordx4 v[0:3], v124, s[0:1]
	global_load_dwordx4 v[4:7], v124, s[0:1] offset:1024
	global_load_dwordx4 v[8:11], v124, s[0:1] offset:2048
	global_load_dwordx4 v[12:15], v124, s[0:1] offset:3072
	global_load_dwordx4 v[32:35], v124, s[4:5]
	global_load_dwordx4 v[36:39], v124, s[4:5] offset:1024
	global_load_dwordx4 v[40:43], v124, s[4:5] offset:2048
	global_load_dwordx4 v[44:47], v124, s[4:5] offset:3072
	global_load_dwordx4 v[48:51], v124, s[8:9]
	global_load_dwordx4 v[52:55], v124, s[8:9] offset:1024
	global_load_dwordx4 v[56:59], v124, s[8:9] offset:2048
	global_load_dwordx4 v[60:63], v124, s[8:9] offset:3072
	s_add_u32 s12, s12, 0x800
	s_waitcnt vmcnt(16)
	v_mul_f32_e32 v121, v16, v16
	v_fmac_f32_e32 v121, v17, v17
	v_fmac_f32_e32 v121, v18, v18
	v_fmac_f32_e32 v121, v19, v19
	v_fmac_f32_e32 v121, v20, v20
	v_fmac_f32_e32 v121, v21, v21
	v_fmac_f32_e32 v121, v22, v22
	v_fmac_f32_e32 v121, v23, v23
	v_fmac_f32_e32 v121, v24, v24
	v_fmac_f32_e32 v121, v25, v25
	v_fmac_f32_e32 v121, v26, v26
	v_fmac_f32_e32 v121, v27, v27
	v_fmac_f32_e32 v121, v28, v28
	v_fmac_f32_e32 v121, v29, v29
	v_fmac_f32_e32 v121, v30, v30
	v_fmac_f32_e32 v121, v31, v31
	s_nop 1
	v_add_f32_dpp v121, v121, v121 quad_perm:[1,0,3,2] row_mask:0xf bank_mask:0xf
	s_nop 1
	v_add_f32_dpp v121, v121, v121 quad_perm:[2,3,0,1] row_mask:0xf bank_mask:0xf
	s_nop 1
	v_add_f32_dpp v121, v121, v121 row_half_mirror row_mask:0xf bank_mask:0xf
	s_nop 1
	v_add_f32_dpp v121, v121, v121 row_mirror row_mask:0xf bank_mask:0xf
	s_nop 1
	v_add_f32_dpp v121, v121, v121 row_bcast:15 row_mask:0xa bank_mask:0xf
	s_nop 1
	v_add_f32_dpp v121, v121, v121 row_bcast:31 row_mask:0xc bank_mask:0xf
	s_nop 1
	v_readlane_b32 s13, v121, 63
	v_mov_b32_e32 v122, 0x3a800000
	s_nop 1
	v_fma_f32 v126, s13, v122, v127
	v_cmp_gt_f32_e32 vcc, 0x800000, v126
	v_mul_f32_e32 v123, 0x4b800000, v126
	v_cndmask_b32_e32 v126, v126, v123, vcc
	v_rsq_f32_e32 v126, v126
	s_nop 0
	v_mul_f32_e32 v123, 0x45800000, v126
	v_cndmask_b32_e32 v126, v126, v123, vcc
	v_mul_f32_e32 v16, v16, v126
	v_mul_f32_e32 v16, v96, v16
	v_add_f32_e32 v64, 1.0, v64
	v_fma_f32 v16, v16, v64, v80
	v_mul_f32_e32 v17, v17, v126
	v_mul_f32_e32 v17, v97, v17
	v_add_f32_e32 v65, 1.0, v65
	v_fma_f32 v17, v17, v65, v81
	v_mul_f32_e32 v18, v18, v126
	v_mul_f32_e32 v18, v98, v18
	v_add_f32_e32 v66, 1.0, v66
	v_fma_f32 v18, v18, v66, v82
	v_mul_f32_e32 v19, v19, v126
	v_mul_f32_e32 v19, v99, v19
	v_add_f32_e32 v67, 1.0, v67
	v_fma_f32 v19, v19, v67, v83
	v_mul_f32_e32 v20, v20, v126
	v_mul_f32_e32 v20, v100, v20
	v_add_f32_e32 v68, 1.0, v68
	v_fma_f32 v20, v20, v68, v84
	v_mul_f32_e32 v21, v21, v126
	v_mul_f32_e32 v21, v101, v21
	v_add_f32_e32 v69, 1.0, v69
	v_fma_f32 v21, v21, v69, v85
	v_mul_f32_e32 v22, v22, v126
	v_mul_f32_e32 v22, v102, v22
	v_add_f32_e32 v70, 1.0, v70
	v_fma_f32 v22, v22, v70, v86
	v_mul_f32_e32 v23, v23, v126
	v_mul_f32_e32 v23, v103, v23
	v_add_f32_e32 v71, 1.0, v71
	v_fma_f32 v23, v23, v71, v87
	v_mul_f32_e32 v24, v24, v126
	v_mul_f32_e32 v24, v104, v24
	v_add_f32_e32 v72, 1.0, v72
	v_fma_f32 v24, v24, v72, v88
	v_mul_f32_e32 v25, v25, v126
	v_mul_f32_e32 v25, v105, v25
	v_add_f32_e32 v73, 1.0, v73
	v_fma_f32 v25, v25, v73, v89
	v_mul_f32_e32 v26, v26, v126
	v_mul_f32_e32 v26, v106, v26
	v_add_f32_e32 v74, 1.0, v74
	v_fma_f32 v26, v26, v74, v90
	v_mul_f32_e32 v27, v27, v126
	v_mul_f32_e32 v27, v107, v27
	v_add_f32_e32 v75, 1.0, v75
	v_fma_f32 v27, v27, v75, v91
	v_mul_f32_e32 v28, v28, v126
	v_mul_f32_e32 v28, v108, v28
	v_add_f32_e32 v76, 1.0, v76
	v_fma_f32 v28, v28, v76, v92
	v_mul_f32_e32 v29, v29, v126
	v_mul_f32_e32 v29, v109, v29
	v_add_f32_e32 v77, 1.0, v77
	v_fma_f32 v29, v29, v77, v93
	v_mul_f32_e32 v30, v30, v126
	v_mul_f32_e32 v30, v110, v30
	v_add_f32_e32 v78, 1.0, v78
	v_fma_f32 v30, v30, v78, v94
	v_mul_f32_e32 v31, v31, v126
	v_mul_f32_e32 v31, v111, v31
	v_add_f32_e32 v79, 1.0, v79
	v_fma_f32 v31, v31, v79, v95
	v_cvt_pk_bf16_f32 v16, v16, v17
	v_cvt_pk_bf16_f32 v17, v18, v19
	global_store_dwordx2 v125, v[16:17], s[14:15]
	v_cvt_pk_bf16_f32 v20, v20, v21
	v_cvt_pk_bf16_f32 v21, v22, v23
	global_store_dwordx2 v125, v[20:21], s[14:15] offset:512
	v_cvt_pk_bf16_f32 v24, v24, v25
	v_cvt_pk_bf16_f32 v25, v26, v27
	global_store_dwordx2 v125, v[24:25], s[14:15] offset:1024
	v_cvt_pk_bf16_f32 v28, v28, v29
	v_cvt_pk_bf16_f32 v29, v30, v31
	global_store_dwordx2 v125, v[28:29], s[14:15] offset:1536
	s_add_u32 s14, s14, 0x400000
	s_addc_u32 s15, s15, 0
	s_lshl_b32 s13, s12, 12
	s_add_u32 s0, s52, s13
	s_addc_u32 s1, s53, 0
	s_lshr_b32 s13, s12, 12
	s_mul_i32 s13, s13, 0x6000
	s_add_u32 s16, s86, s13
	s_addc_u32 s17, s87, 0
	s_add_u32 s4, s16, 0x1000
	s_addc_u32 s5, s17, 0
	s_add_u32 s8, s16, 0x0
	s_addc_u32 s9, s17, 0
	global_load_dwordx4 v[16:19], v124, s[0:1]
	global_load_dwordx4 v[20:23], v124, s[0:1] offset:1024
	global_load_dwordx4 v[24:27], v124, s[0:1] offset:2048
	global_load_dwordx4 v[28:31], v124, s[0:1] offset:3072
	global_load_dwordx4 v[64:67], v124, s[4:5]
	global_load_dwordx4 v[68:71], v124, s[4:5] offset:1024
	global_load_dwordx4 v[72:75], v124, s[4:5] offset:2048
	global_load_dwordx4 v[76:79], v124, s[4:5] offset:3072
	global_load_dwordx4 v[80:83], v124, s[8:9]
	global_load_dwordx4 v[84:87], v124, s[8:9] offset:1024
	global_load_dwordx4 v[88:91], v124, s[8:9] offset:2048
	global_load_dwordx4 v[92:95], v124, s[8:9] offset:3072
	s_add_u32 s12, s12, 0x800
	s_add_u32 s18, s18, 1
	s_branch .Lnorm1_loop
; DEV void phase_norm_adaln(const float* __restrict__ X, const float* __restrict__ gvec, const float* __restrict__ mod,
;                           int bg0, int L, int sh_off, int sc_off, u16* __restrict__ H) {
;     ...
;     for (int j = 0; j < RB; ++j) {
;       const int row = row0 + j * stride;
;       if (row < NTOK) {
;         const float rstd = rsqrtf(ss[j] * (1.f / 1024.f) + EPSF);
;         const float* mrow = mod + (long)(bg0 + row / L) * DIN;
; #pragma unroll
;         for (int i = 0; i < 4; ++i) {
;           const int k = lane * 4 + 256 * i;
;           const float4 g = *(const float4*)(gvec + k);
;           const float4 sc = *(const float4*)(mrow + sc_off + k);
;           const float4 sh = *(const float4*)(mrow + sh_off + k);
;           const float o0 = v[j][i].x * rstd * g.x * (1.f + sc.x) + sh.x;
;           const float o1 = v[j][i].y * rstd * g.y * (1.f + sc.y) + sh.y;
;           const float o2 = v[j][i].z * rstd * g.z * (1.f + sc.z) + sh.z;
;           const float o3 = v[j][i].w * rstd * g.w * (1.f + sc.w) + sh.w;
;           *(uint2*)(H + (long)row * D + k) = make_uint2(pack2(o0, o1), pack2(o2, o3));
;         }
;       }
;     }
.Lnorm1_tail:
	s_waitcnt vmcnt(4)
	v_mul_f32_e32 v121, v16, v16
	v_fmac_f32_e32 v121, v17, v17
	v_fmac_f32_e32 v121, v18, v18
	v_fmac_f32_e32 v121, v19, v19
	v_fmac_f32_e32 v121, v20, v20
	v_fmac_f32_e32 v121, v21, v21
	v_fmac_f32_e32 v121, v22, v22
	v_fmac_f32_e32 v121, v23, v23
	v_fmac_f32_e32 v121, v24, v24
	v_fmac_f32_e32 v121, v25, v25
	v_fmac_f32_e32 v121, v26, v26
	v_fmac_f32_e32 v121, v27, v27
	v_fmac_f32_e32 v121, v28, v28
	v_fmac_f32_e32 v121, v29, v29
	v_fmac_f32_e32 v121, v30, v30
	v_fmac_f32_e32 v121, v31, v31
	s_nop 1
	v_add_f32_dpp v121, v121, v121 quad_perm:[1,0,3,2] row_mask:0xf bank_mask:0xf
	s_nop 1
	v_add_f32_dpp v121, v121, v121 quad_perm:[2,3,0,1] row_mask:0xf bank_mask:0xf
	s_nop 1
	v_add_f32_dpp v121, v121, v121 row_half_mirror row_mask:0xf bank_mask:0xf
	s_nop 1
	v_add_f32_dpp v121, v121, v121 row_mirror row_mask:0xf bank_mask:0xf
	s_nop 1
	v_add_f32_dpp v121, v121, v121 row_bcast:15 row_mask:0xa bank_mask:0xf
	s_nop 1
	v_add_f32_dpp v121, v121, v121 row_bcast:31 row_mask:0xc bank_mask:0xf
	s_nop 1
	v_readlane_b32 s13, v121, 63
	v_mov_b32_e32 v122, 0x3a800000
	s_nop 1
	v_fma_f32 v126, s13, v122, v127
	v_cmp_gt_f32_e32 vcc, 0x800000, v126
	v_mul_f32_e32 v123, 0x4b800000, v126
	v_cndmask_b32_e32 v126, v126, v123, vcc
	v_rsq_f32_e32 v126, v126
	s_nop 0
	v_mul_f32_e32 v123, 0x45800000, v126
	v_cndmask_b32_e32 v126, v126, v123, vcc
	v_mul_f32_e32 v16, v16, v126
	v_mul_f32_e32 v16, v96, v16
	v_add_f32_e32 v64, 1.0, v64
	v_fma_f32 v16, v16, v64, v80
	v_mul_f32_e32 v17, v17, v126
	v_mul_f32_e32 v17, v97, v17
	v_add_f32_e32 v65, 1.0, v65
	v_fma_f32 v17, v17, v65, v81
	v_mul_f32_e32 v18, v18, v126
	v_mul_f32_e32 v18, v98, v18
	v_add_f32_e32 v66, 1.0, v66
	v_fma_f32 v18, v18, v66, v82
	v_mul_f32_e32 v19, v19, v126
	v_mul_f32_e32 v19, v99, v19
	v_add_f32_e32 v67, 1.0, v67
	v_fma_f32 v19, v19, v67, v83
	v_mul_f32_e32 v20, v20, v126
	v_mul_f32_e32 v20, v100, v20
	v_add_f32_e32 v68, 1.0, v68
	v_fma_f32 v20, v20, v68, v84
	v_mul_f32_e32 v21, v21, v126
	v_mul_f32_e32 v21, v101, v21
	v_add_f32_e32 v69, 1.0, v69
	v_fma_f32 v21, v21, v69, v85
	v_mul_f32_e32 v22, v22, v126
	v_mul_f32_e32 v22, v102, v22
	v_add_f32_e32 v70, 1.0, v70
	v_fma_f32 v22, v22, v70, v86
	v_mul_f32_e32 v23, v23, v126
	v_mul_f32_e32 v23, v103, v23
	v_add_f32_e32 v71, 1.0, v71
	v_fma_f32 v23, v23, v71, v87
	v_mul_f32_e32 v24, v24, v126
	v_mul_f32_e32 v24, v104, v24
	v_add_f32_e32 v72, 1.0, v72
	v_fma_f32 v24, v24, v72, v88
	v_mul_f32_e32 v25, v25, v126
	v_mul_f32_e32 v25, v105, v25
	v_add_f32_e32 v73, 1.0, v73
	v_fma_f32 v25, v25, v73, v89
	v_mul_f32_e32 v26, v26, v126
	v_mul_f32_e32 v26, v106, v26
	v_add_f32_e32 v74, 1.0, v74
	v_fma_f32 v26, v26, v74, v90
	v_mul_f32_e32 v27, v27, v126
	v_mul_f32_e32 v27, v107, v27
	v_add_f32_e32 v75, 1.0, v75
	v_fma_f32 v27, v27, v75, v91
	v_mul_f32_e32 v28, v28, v126
	v_mul_f32_e32 v28, v108, v28
	v_add_f32_e32 v76, 1.0, v76
	v_fma_f32 v28, v28, v76, v92
	v_mul_f32_e32 v29, v29, v126
	v_mul_f32_e32 v29, v109, v29
	v_add_f32_e32 v77, 1.0, v77
	v_fma_f32 v29, v29, v77, v93
	v_mul_f32_e32 v30, v30, v126
	v_mul_f32_e32 v30, v110, v30
	v_add_f32_e32 v78, 1.0, v78
	v_fma_f32 v30, v30, v78, v94
	v_mul_f32_e32 v31, v31, v126
	v_mul_f32_e32 v31, v111, v31
	v_add_f32_e32 v79, 1.0, v79
	v_fma_f32 v31, v31, v79, v95
	v_cvt_pk_bf16_f32 v16, v16, v17
	v_cvt_pk_bf16_f32 v17, v18, v19
	global_store_dwordx2 v125, v[16:17], s[14:15]
	v_cvt_pk_bf16_f32 v20, v20, v21
	v_cvt_pk_bf16_f32 v21, v22, v23
	global_store_dwordx2 v125, v[20:21], s[14:15] offset:512
	v_cvt_pk_bf16_f32 v24, v24, v25
	v_cvt_pk_bf16_f32 v25, v26, v27
	global_store_dwordx2 v125, v[24:25], s[14:15] offset:1024
	v_cvt_pk_bf16_f32 v28, v28, v29
	v_cvt_pk_bf16_f32 v29, v30, v31
	global_store_dwordx2 v125, v[28:29], s[14:15] offset:1536
	s_add_u32 s14, s14, 0x400000
	s_addc_u32 s15, s15, 0

; DEV int tidx() { return tidx_full() & 255; }
; DEV void norm_adaln_rows(const float* __restrict__ X, const float* __restrict__ gvec, const float* __restrict__ mod,
;                          int bg0, int L, int sh_off, int sc_off, u16* __restrict__ H, int rbeg) {
;   const int tid = tidx();
;   const int wave = tid >> 6, lane = tid & 63;
;   for (int jb = 0; jb < 16; jb += 4) {
;     float4 v[4][4];
;     float ss[4];
; #pragma unroll
;     for (int j = 0; j < 4; ++j) {
;       const float* x = X + (long)(rbeg + wave + 4 * (jb + j)) * D;
; #pragma unroll
;       for (int i = 0; i < 4; ++i) v[j][i] = *(const float4*)(x + lane * 4 + 256 * i);
;     }
; #pragma unroll
;     for (int j = 0; j < 4; ++j) {
;       float t = 0.f;
; #pragma unroll
;       for (int i = 0; i < 4; ++i) t += v[j][i].x * v[j][i].x + v[j][i].y * v[j][i].y + v[j][i].z * v[j][i].z + v[j][i].w * v[j][i].w;
;       ss[j] = wave_sum(t);
;     }
; #pragma unroll
;     for (int j = 0; j < 4; ++j) {
;       const int row = rbeg + wave + 4 * (jb + j);
;       const float rstd = rsqrtf(ss[j] * (1.f / 1024.f) + EPSF);
;       const float* mrow = mod + (long)(bg0 + row / L) * DIN;
; #pragma unroll
;       for (int i = 0; i < 4; ++i) {
;         const int k = lane * 4 + 256 * i;
;         const float4 g = *(const float4*)(gvec + k);
;         const float4 sc = *(const float4*)(mrow + sc_off + k);
;         const float4 sh = *(const float4*)(mrow + sh_off + k);
;         const float o0 = v[j][i].x * rstd * g.x * (1.f + sc.x) + sh.x;
;         const float o1 = v[j][i].y * rstd * g.y * (1.f + sc.y) + sh.y;
;         const float o2 = v[j][i].z * rstd * g.z * (1.f + sc.z) + sh.z;
;         const float o3 = v[j][i].w * rstd * g.w * (1.f + sc.w) + sh.w;
;         *(uint2*)(H + (long)row * D + k) = make_uint2(pack2(o0, o1), pack2(o2, o3));
;       }
;     }
;   }
; }
; DEV void phase_p2_naive(const Params& p, int g, char* hsm) {
;     ...
;   for (;;) {
;     __syncthreads();
;     if (threadIdx.x == 0) s_item = (int)atomicAdd(cnt2, 2u);
;     __syncthreads();
;     const int it = s_item + half;
;     if (it >= 512) break;
;     if (g == 0) norm_adaln_rows(p.in[I_XS], p.in[I_N1G], mod, 8, 8192, 0, 1024, (u16*)(p.out + (size_t)NTOK * D), it * 64);
.LBB0_818:
	s_and_b64 vcc, exec, s[0:1]
	s_mov_b64 s[0:1], 0x1000
	s_mov_b32 s36, 0x3a800000
	s_mov_b32 s38, 0x358637bd
	s_cbranch_vccz .LBB0_807
	v_readfirstlane_b32 s12, v202
	v_readlane_b32 s14, v249, 12
	v_readlane_b32 s15, v249, 13
	v_readlane_b32 s16, v249, 2
	v_readlane_b32 s17, v249, 3
	s_bfe_u32 s12, s12, 0x20006
	s_add_u32 s12, s12, s4
	v_and_b32_e32 v115, 63, v202
	v_lshlrev_b32_e32 v116, 3, v115
	v_lshlrev_b32_e32 v115, 4, v115
	global_load_dwordx4 v[96:99], v115, s[14:15]
	global_load_dwordx4 v[100:103], v115, s[14:15] offset:1024
	global_load_dwordx4 v[104:107], v115, s[14:15] offset:2048
	global_load_dwordx4 v[108:111], v115, s[14:15] offset:3072
	s_lshl_b32 s13, s12, 11
	s_add_u32 s10, s28, s13
	s_addc_u32 s11, s29, 0
	s_lshl_b32 s13, s12, 12
	s_add_u32 s0, s16, s13
	s_addc_u32 s1, s17, 0
	s_lshr_b32 s13, s12, 13
	s_add_u32 s13, s13, 8
	s_mul_i32 s13, s13, 0x6000
	s_add_u32 s18, s86, s13
	s_addc_u32 s19, s87, 0
	s_add_u32 s6, s18, 0x1000
	s_addc_u32 s7, s19, 0
	s_add_u32 s8, s18, 0x0
	s_addc_u32 s9, s19, 0
	global_load_dwordx4 v[0:3], v115, s[0:1]
	global_load_dwordx4 v[4:7], v115, s[0:1] offset:1024
	global_load_dwordx4 v[8:11], v115, s[0:1] offset:2048
	global_load_dwordx4 v[12:15], v115, s[0:1] offset:3072
	global_load_dwordx4 v[32:35], v115, s[6:7]
	global_load_dwordx4 v[36:39], v115, s[6:7] offset:1024
	global_load_dwordx4 v[40:43], v115, s[6:7] offset:2048
	global_load_dwordx4 v[44:47], v115, s[6:7] offset:3072
	global_load_dwordx4 v[48:51], v115, s[8:9]
	global_load_dwordx4 v[52:55], v115, s[8:9] offset:1024
	global_load_dwordx4 v[56:59], v115, s[8:9] offset:2048
	global_load_dwordx4 v[60:63], v115, s[8:9] offset:3072
	s_add_u32 s12, s12, 0x4
	s_lshl_b32 s13, s12, 12
	s_add_u32 s0, s16, s13
	s_addc_u32 s1, s17, 0
	s_lshr_b32 s13, s12, 13
	s_add_u32 s13, s13, 8
	s_mul_i32 s13, s13, 0x6000
	s_add_u32 s18, s86, s13
	s_addc_u32 s19, s87, 0
	s_add_u32 s6, s18, 0x1000
	s_addc_u32 s7, s19, 0
	s_add_u32 s8, s18, 0x0
	s_addc_u32 s9, s19, 0
	global_load_dwordx4 v[16:19], v115, s[0:1]
	global_load_dwordx4 v[20:23], v115, s[0:1] offset:1024
	global_load_dwordx4 v[24:27], v115, s[0:1] offset:2048
	global_load_dwordx4 v[28:31], v115, s[0:1] offset:3072
	global_load_dwordx4 v[64:67], v115, s[6:7]
	global_load_dwordx4 v[68:71], v115, s[6:7] offset:1024
	global_load_dwordx4 v[72:75], v115, s[6:7] offset:2048
	global_load_dwordx4 v[76:79], v115, s[6:7] offset:3072
	global_load_dwordx4 v[80:83], v115, s[8:9]
	global_load_dwordx4 v[84:87], v115, s[8:9] offset:1024
	global_load_dwordx4 v[88:91], v115, s[8:9] offset:2048
	global_load_dwordx4 v[92:95], v115, s[8:9] offset:3072
	s_add_u32 s12, s12, 0x4
	s_mov_b32 s20, 0
.Lnfill_loop:
	s_waitcnt vmcnt(12)
	v_mul_f32_e32 v112, v0, v0
	v_fmac_f32_e32 v112, v1, v1
	v_fmac_f32_e32 v112, v2, v2
	v_fmac_f32_e32 v112, v3, v3
	v_fmac_f32_e32 v112, v4, v4
	v_fmac_f32_e32 v112, v5, v5
	v_fmac_f32_e32 v112, v6, v6
	v_fmac_f32_e32 v112, v7, v7
	v_fmac_f32_e32 v112, v8, v8
	v_fmac_f32_e32 v112, v9, v9
	v_fmac_f32_e32 v112, v10, v10
	v_fmac_f32_e32 v112, v11, v11
	v_fmac_f32_e32 v112, v12, v12
	v_fmac_f32_e32 v112, v13, v13
	v_fmac_f32_e32 v112, v14, v14
	v_fmac_f32_e32 v112, v15, v15
	s_nop 1
	v_add_f32_dpp v112, v112, v112 quad_perm:[1,0,3,2] row_mask:0xf bank_mask:0xf
	s_nop 1
	v_add_f32_dpp v112, v112, v112 quad_perm:[2,3,0,1] row_mask:0xf bank_mask:0xf
	s_nop 1
	v_add_f32_dpp v112, v112, v112 row_half_mirror row_mask:0xf bank_mask:0xf
	s_nop 1
	v_add_f32_dpp v112, v112, v112 row_mirror row_mask:0xf bank_mask:0xf
	s_nop 1
	v_add_f32_dpp v112, v112, v112 row_bcast:15 row_mask:0xa bank_mask:0xf
	s_nop 1
	v_add_f32_dpp v112, v112, v112 row_bcast:31 row_mask:0xc bank_mask:0xf
	s_nop 1
	v_readlane_b32 s13, v112, 63
	v_mov_b32_e32 v113, 0x3a800000
	s_nop 1
	v_fma_f32 v117, s13, v113, v212
	v_cmp_gt_f32_e32 vcc, 0x800000, v117
	v_mul_f32_e32 v114, 0x4b800000, v117
	v_cndmask_b32_e32 v117, v117, v114, vcc
	v_rsq_f32_e32 v117, v117
	s_nop 0
	v_mul_f32_e32 v114, 0x45800000, v117
	v_cndmask_b32_e32 v117, v117, v114, vcc
	v_mul_f32_e32 v0, v0, v117
	v_mul_f32_e32 v0, v96, v0
	v_add_f32_e32 v32, 1.0, v32
	v_fma_f32 v0, v0, v32, v48
	v_mul_f32_e32 v1, v1, v117
	v_mul_f32_e32 v1, v97, v1
	v_add_f32_e32 v33, 1.0, v33
	v_fma_f32 v1, v1, v33, v49
	v_mul_f32_e32 v2, v2, v117
	v_mul_f32_e32 v2, v98, v2
	v_add_f32_e32 v34, 1.0, v34
	v_fma_f32 v2, v2, v34, v50
	v_mul_f32_e32 v3, v3, v117
	v_mul_f32_e32 v3, v99, v3
	v_add_f32_e32 v35, 1.0, v35
	v_fma_f32 v3, v3, v35, v51
	v_mul_f32_e32 v4, v4, v117
	v_mul_f32_e32 v4, v100, v4
	v_add_f32_e32 v36, 1.0, v36
	v_fma_f32 v4, v4, v36, v52
	v_mul_f32_e32 v5, v5, v117
	v_mul_f32_e32 v5, v101, v5
	v_add_f32_e32 v37, 1.0, v37
	v_fma_f32 v5, v5, v37, v53
	v_mul_f32_e32 v6, v6, v117
	v_mul_f32_e32 v6, v102, v6
	v_add_f32_e32 v38, 1.0, v38
	v_fma_f32 v6, v6, v38, v54
	v_mul_f32_e32 v7, v7, v117
	v_mul_f32_e32 v7, v103, v7
	v_add_f32_e32 v39, 1.0, v39
	v_fma_f32 v7, v7, v39, v55
	v_mul_f32_e32 v8, v8, v117
	v_mul_f32_e32 v8, v104, v8
	v_add_f32_e32 v40, 1.0, v40
	v_fma_f32 v8, v8, v40, v56
	v_mul_f32_e32 v9, v9, v117
	v_mul_f32_e32 v9, v105, v9
	v_add_f32_e32 v41, 1.0, v41
	v_fma_f32 v9, v9, v41, v57
	v_mul_f32_e32 v10, v10, v117
	v_mul_f32_e32 v10, v106, v10
	v_add_f32_e32 v42, 1.0, v42
	v_fma_f32 v10, v10, v42, v58
	v_mul_f32_e32 v11, v11, v117
	v_mul_f32_e32 v11, v107, v11
	v_add_f32_e32 v43, 1.0, v43
	v_fma_f32 v11, v11, v43, v59
	v_mul_f32_e32 v12, v12, v117
	v_mul_f32_e32 v12, v108, v12
	v_add_f32_e32 v44, 1.0, v44
	v_fma_f32 v12, v12, v44, v60
	v_mul_f32_e32 v13, v13, v117
	v_mul_f32_e32 v13, v109, v13
	v_add_f32_e32 v45, 1.0, v45
	v_fma_f32 v13, v13, v45, v61
	v_mul_f32_e32 v14, v14, v117
	v_mul_f32_e32 v14, v110, v14
	v_add_f32_e32 v46, 1.0, v46
	v_fma_f32 v14, v14, v46, v62
	v_mul_f32_e32 v15, v15, v117
	v_mul_f32_e32 v15, v111, v15
	v_add_f32_e32 v47, 1.0, v47
	v_fma_f32 v15, v15, v47, v63
	v_cvt_pk_bf16_f32 v0, v0, v1
	v_cvt_pk_bf16_f32 v1, v2, v3
	global_store_dwordx2 v116, v[0:1], s[10:11]
	v_cvt_pk_bf16_f32 v4, v4, v5
	v_cvt_pk_bf16_f32 v5, v6, v7
	global_store_dwordx2 v116, v[4:5], s[10:11] offset:512
	v_cvt_pk_bf16_f32 v8, v8, v9
	v_cvt_pk_bf16_f32 v9, v10, v11
	global_store_dwordx2 v116, v[8:9], s[10:11] offset:1024
	v_cvt_pk_bf16_f32 v12, v12, v13
	v_cvt_pk_bf16_f32 v13, v14, v15
	global_store_dwordx2 v116, v[12:13], s[10:11] offset:1536
	s_add_u32 s10, s10, 0x2000
	s_addc_u32 s11, s11, 0
	s_cmp_eq_u32 s20, 7
	s_cbranch_scc1 .Lnfill_tail
; DEV void norm_adaln_rows(const float* __restrict__ X, const float* __restrict__ gvec, const float* __restrict__ mod,
;                          int bg0, int L, int sh_off, int sc_off, u16* __restrict__ H, int rbeg) {
;     ...
;   for (int jb = 0; jb < 16; jb += 4) {
;     float4 v[4][4];
;     float ss[4];
; #pragma unroll
;     for (int j = 0; j < 4; ++j) {
;       const float* x = X + (long)(rbeg + wave + 4 * (jb + j)) * D;
; #pragma unroll
;       for (int i = 0; i < 4; ++i) v[j][i] = *(const float4*)(x + lane * 4 + 256 * i);
;     }
; #pragma unroll
;     for (int j = 0; j < 4; ++j) {
;       float t = 0.f;
; #pragma unroll
;       for (int i = 0; i < 4; ++i) t += v[j][i].x * v[j][i].x + v[j][i].y * v[j][i].y + v[j][i].z * v[j][i].z + v[j][i].w * v[j][i].w;
;       ss[j] = wave_sum(t);
;     }
; #pragma unroll
;     for (int j = 0; j < 4; ++j) {
;       const int row = rbeg + wave + 4 * (jb + j);
;       const float rstd = rsqrtf(ss[j] * (1.f / 1024.f) + EPSF);
;       const float* mrow = mod + (long)(bg0 + row / L) * DIN;
; #pragma unroll
;       for (int i = 0; i < 4; ++i) {
;         const int k = lane * 4 + 256 * i;
;         const float4 g = *(const float4*)(gvec + k);
;         const float4 sc = *(const float4*)(mrow + sc_off + k);
;         const float4 sh = *(const float4*)(mrow + sh_off + k);
;         const float o0 = v[j][i].x * rstd * g.x * (1.f + sc.x) + sh.x;
;         const float o1 = v[j][i].y * rstd * g.y * (1.f + sc.y) + sh.y;
;         const float o2 = v[j][i].z * rstd * g.z * (1.f + sc.z) + sh.z;
;         const float o3 = v[j][i].w * rstd * g.w * (1.f + sc.w) + sh.w;
;         *(uint2*)(H + (long)row * D + k) = make_uint2(pack2(o0, o1), pack2(o2, o3));
;       }
;     }
;   }
	s_lshl_b32 s13, s12, 12
	s_add_u32 s0, s16, s13
	s_addc_u32 s1, s17, 0
	s_lshr_b32 s13, s12, 13
	s_add_u32 s13, s13, 8
	s_mul_i32 s13, s13, 0x6000
	s_add_u32 s18, s86, s13
	s_addc_u32 s19, s87, 0
	s_add_u32 s6, s18, 0x1000
	s_addc_u32 s7, s19, 0
	s_add_u32 s8, s18, 0x0
	s_addc_u32 s9, s19, 0
	global_load_dwordx4 v[0:3], v115, s[0:1]
	global_load_dwordx4 v[4:7], v115, s[0:1] offset:1024
	global_load_dwordx4 v[8:11], v115, s[0:1] offset:2048
	global_load_dwordx4 v[12:15], v115, s[0:1] offset:3072
	global_load_dwordx4 v[32:35], v115, s[6:7]
	global_load_dwordx4 v[36:39], v115, s[6:7] offset:1024
	global_load_dwordx4 v[40:43], v115, s[6:7] offset:2048
	global_load_dwordx4 v[44:47], v115, s[6:7] offset:3072
	global_load_dwordx4 v[48:51], v115, s[8:9]
	global_load_dwordx4 v[52:55], v115, s[8:9] offset:1024
	global_load_dwordx4 v[56:59], v115, s[8:9] offset:2048
	global_load_dwordx4 v[60:63], v115, s[8:9] offset:3072
	s_add_u32 s12, s12, 0x4
	s_waitcnt vmcnt(16)
	v_mul_f32_e32 v112, v16, v16
	v_fmac_f32_e32 v112, v17, v17
	v_fmac_f32_e32 v112, v18, v18
	v_fmac_f32_e32 v112, v19, v19
	v_fmac_f32_e32 v112, v20, v20
	v_fmac_f32_e32 v112, v21, v21
	v_fmac_f32_e32 v112, v22, v22
	v_fmac_f32_e32 v112, v23, v23
	v_fmac_f32_e32 v112, v24, v24
	v_fmac_f32_e32 v112, v25, v25
	v_fmac_f32_e32 v112, v26, v26
	v_fmac_f32_e32 v112, v27, v27
	v_fmac_f32_e32 v112, v28, v28
	v_fmac_f32_e32 v112, v29, v29
	v_fmac_f32_e32 v112, v30, v30
	v_fmac_f32_e32 v112, v31, v31
	s_nop 1
	v_add_f32_dpp v112, v112, v112 quad_perm:[1,0,3,2] row_mask:0xf bank_mask:0xf
	s_nop 1
	v_add_f32_dpp v112, v112, v112 quad_perm:[2,3,0,1] row_mask:0xf bank_mask:0xf
	s_nop 1
	v_add_f32_dpp v112, v112, v112 row_half_mirror row_mask:0xf bank_mask:0xf
	s_nop 1
	v_add_f32_dpp v112, v112, v112 row_mirror row_mask:0xf bank_mask:0xf
	s_nop 1
	v_add_f32_dpp v112, v112, v112 row_bcast:15 row_mask:0xa bank_mask:0xf
	s_nop 1
	v_add_f32_dpp v112, v112, v112 row_bcast:31 row_mask:0xc bank_mask:0xf
	s_nop 1
	v_readlane_b32 s13, v112, 63
	v_mov_b32_e32 v113, 0x3a800000
	s_nop 1
	v_fma_f32 v117, s13, v113, v212
	v_cmp_gt_f32_e32 vcc, 0x800000, v117
	v_mul_f32_e32 v114, 0x4b800000, v117
	v_cndmask_b32_e32 v117, v117, v114, vcc
	v_rsq_f32_e32 v117, v117
	s_nop 0
	v_mul_f32_e32 v114, 0x45800000, v117
	v_cndmask_b32_e32 v117, v117, v114, vcc
	v_mul_f32_e32 v16, v16, v117
	v_mul_f32_e32 v16, v96, v16
	v_add_f32_e32 v64, 1.0, v64
	v_fma_f32 v16, v16, v64, v80
	v_mul_f32_e32 v17, v17, v117
	v_mul_f32_e32 v17, v97, v17
	v_add_f32_e32 v65, 1.0, v65
	v_fma_f32 v17, v17, v65, v81
	v_mul_f32_e32 v18, v18, v117
	v_mul_f32_e32 v18, v98, v18
	v_add_f32_e32 v66, 1.0, v66
	v_fma_f32 v18, v18, v66, v82
	v_mul_f32_e32 v19, v19, v117
	v_mul_f32_e32 v19, v99, v19
	v_add_f32_e32 v67, 1.0, v67
	v_fma_f32 v19, v19, v67, v83
	v_mul_f32_e32 v20, v20, v117
	v_mul_f32_e32 v20, v100, v20
	v_add_f32_e32 v68, 1.0, v68
	v_fma_f32 v20, v20, v68, v84
	v_mul_f32_e32 v21, v21, v117
	v_mul_f32_e32 v21, v101, v21
	v_add_f32_e32 v69, 1.0, v69
	v_fma_f32 v21, v21, v69, v85
	v_mul_f32_e32 v22, v22, v117
	v_mul_f32_e32 v22, v102, v22
	v_add_f32_e32 v70, 1.0, v70
	v_fma_f32 v22, v22, v70, v86
	v_mul_f32_e32 v23, v23, v117
	v_mul_f32_e32 v23, v103, v23
	v_add_f32_e32 v71, 1.0, v71
	v_fma_f32 v23, v23, v71, v87
	v_mul_f32_e32 v24, v24, v117
	v_mul_f32_e32 v24, v104, v24
	v_add_f32_e32 v72, 1.0, v72
	v_fma_f32 v24, v24, v72, v88
	v_mul_f32_e32 v25, v25, v117
	v_mul_f32_e32 v25, v105, v25
	v_add_f32_e32 v73, 1.0, v73
	v_fma_f32 v25, v25, v73, v89
	v_mul_f32_e32 v26, v26, v117
	v_mul_f32_e32 v26, v106, v26
	v_add_f32_e32 v74, 1.0, v74
	v_fma_f32 v26, v26, v74, v90
	v_mul_f32_e32 v27, v27, v117
	v_mul_f32_e32 v27, v107, v27
	v_add_f32_e32 v75, 1.0, v75
	v_fma_f32 v27, v27, v75, v91
	v_mul_f32_e32 v28, v28, v117
	v_mul_f32_e32 v28, v108, v28
	v_add_f32_e32 v76, 1.0, v76
	v_fma_f32 v28, v28, v76, v92
	v_mul_f32_e32 v29, v29, v117
	v_mul_f32_e32 v29, v109, v29
	v_add_f32_e32 v77, 1.0, v77
	v_fma_f32 v29, v29, v77, v93
	v_mul_f32_e32 v30, v30, v117
	v_mul_f32_e32 v30, v110, v30
	v_add_f32_e32 v78, 1.0, v78
	v_fma_f32 v30, v30, v78, v94
	v_mul_f32_e32 v31, v31, v117
	v_mul_f32_e32 v31, v111, v31
	v_add_f32_e32 v79, 1.0, v79
	v_fma_f32 v31, v31, v79, v95
	v_cvt_pk_bf16_f32 v16, v16, v17
	v_cvt_pk_bf16_f32 v17, v18, v19
	global_store_dwordx2 v116, v[16:17], s[10:11]
	v_cvt_pk_bf16_f32 v20, v20, v21
	v_cvt_pk_bf16_f32 v21, v22, v23
	global_store_dwordx2 v116, v[20:21], s[10:11] offset:512
	v_cvt_pk_bf16_f32 v24, v24, v25
	v_cvt_pk_bf16_f32 v25, v26, v27
	global_store_dwordx2 v116, v[24:25], s[10:11] offset:1024
	v_cvt_pk_bf16_f32 v28, v28, v29
	v_cvt_pk_bf16_f32 v29, v30, v31
	global_store_dwordx2 v116, v[28:29], s[10:11] offset:1536
	s_add_u32 s10, s10, 0x2000
	s_addc_u32 s11, s11, 0
	s_lshl_b32 s13, s12, 12
	s_add_u32 s0, s16, s13
	s_addc_u32 s1, s17, 0
	s_lshr_b32 s13, s12, 13
	s_add_u32 s13, s13, 8
	s_mul_i32 s13, s13, 0x6000
	s_add_u32 s18, s86, s13
	s_addc_u32 s19, s87, 0
	s_add_u32 s6, s18, 0x1000
	s_addc_u32 s7, s19, 0
	s_add_u32 s8, s18, 0x0
	s_addc_u32 s9, s19, 0
	global_load_dwordx4 v[16:19], v115, s[0:1]
	global_load_dwordx4 v[20:23], v115, s[0:1] offset:1024
	global_load_dwordx4 v[24:27], v115, s[0:1] offset:2048
	global_load_dwordx4 v[28:31], v115, s[0:1] offset:3072
	global_load_dwordx4 v[64:67], v115, s[6:7]
	global_load_dwordx4 v[68:71], v115, s[6:7] offset:1024
	global_load_dwordx4 v[72:75], v115, s[6:7] offset:2048
	global_load_dwordx4 v[76:79], v115, s[6:7] offset:3072
	global_load_dwordx4 v[80:83], v115, s[8:9]
	global_load_dwordx4 v[84:87], v115, s[8:9] offset:1024
	global_load_dwordx4 v[88:91], v115, s[8:9] offset:2048
	global_load_dwordx4 v[92:95], v115, s[8:9] offset:3072
	s_add_u32 s12, s12, 0x4
	s_add_u32 s20, s20, 1
	s_branch .Lnfill_loop
; DEV void norm_adaln_rows(const float* __restrict__ X, const float* __restrict__ gvec, const float* __restrict__ mod,
;                          int bg0, int L, int sh_off, int sc_off, u16* __restrict__ H, int rbeg) {
;     ...
; #pragma unroll
;     for (int j = 0; j < 4; ++j) {
;       const int row = rbeg + wave + 4 * (jb + j);
;       const float rstd = rsqrtf(ss[j] * (1.f / 1024.f) + EPSF);
;       const float* mrow = mod + (long)(bg0 + row / L) * DIN;
; #pragma unroll
;       for (int i = 0; i < 4; ++i) {
;         const int k = lane * 4 + 256 * i;
;         const float4 g = *(const float4*)(gvec + k);
;         const float4 sc = *(const float4*)(mrow + sc_off + k);
;         const float4 sh = *(const float4*)(mrow + sh_off + k);
;         const float o0 = v[j][i].x * rstd * g.x * (1.f + sc.x) + sh.x;
;         const float o1 = v[j][i].y * rstd * g.y * (1.f + sc.y) + sh.y;
;         const float o2 = v[j][i].z * rstd * g.z * (1.f + sc.z) + sh.z;
;         const float o3 = v[j][i].w * rstd * g.w * (1.f + sc.w) + sh.w;
;         *(uint2*)(H + (long)row * D + k) = make_uint2(pack2(o0, o1), pack2(o2, o3));
;       }
;     }
;   }
; DEV void phase_p2_naive(const Params& p, int g, char* hsm) {
;     ...
;   for (;;) {
;     __syncthreads();
;     if (threadIdx.x == 0) s_item = (int)atomicAdd(cnt2, 2u);
;     __syncthreads();
;     const int it = s_item + half;
;     if (it >= 512) break;
;     if (g == 0) norm_adaln_rows(p.in[I_XS], p.in[I_N1G], mod, 8, 8192, 0, 1024, (u16*)(p.out + (size_t)NTOK * D), it * 64);
;     else final_norm_rows(p.out, p.in[I_FING], it * 64);
;   }
.Lnfill_tail:
	s_waitcnt vmcnt(4)
	v_mul_f32_e32 v112, v16, v16
	v_fmac_f32_e32 v112, v17, v17
	v_fmac_f32_e32 v112, v18, v18
	v_fmac_f32_e32 v112, v19, v19
	v_fmac_f32_e32 v112, v20, v20
	v_fmac_f32_e32 v112, v21, v21
	v_fmac_f32_e32 v112, v22, v22
	v_fmac_f32_e32 v112, v23, v23
	v_fmac_f32_e32 v112, v24, v24
	v_fmac_f32_e32 v112, v25, v25
	v_fmac_f32_e32 v112, v26, v26
	v_fmac_f32_e32 v112, v27, v27
	v_fmac_f32_e32 v112, v28, v28
	v_fmac_f32_e32 v112, v29, v29
	v_fmac_f32_e32 v112, v30, v30
	v_fmac_f32_e32 v112, v31, v31
	s_nop 1
	v_add_f32_dpp v112, v112, v112 quad_perm:[1,0,3,2] row_mask:0xf bank_mask:0xf
	s_nop 1
	v_add_f32_dpp v112, v112, v112 quad_perm:[2,3,0,1] row_mask:0xf bank_mask:0xf
	s_nop 1
	v_add_f32_dpp v112, v112, v112 row_half_mirror row_mask:0xf bank_mask:0xf
	s_nop 1
	v_add_f32_dpp v112, v112, v112 row_mirror row_mask:0xf bank_mask:0xf
	s_nop 1
	v_add_f32_dpp v112, v112, v112 row_bcast:15 row_mask:0xa bank_mask:0xf
	s_nop 1
	v_add_f32_dpp v112, v112, v112 row_bcast:31 row_mask:0xc bank_mask:0xf
	s_nop 1
	v_readlane_b32 s13, v112, 63
	v_mov_b32_e32 v113, 0x3a800000
	s_nop 1
	v_fma_f32 v117, s13, v113, v212
	v_cmp_gt_f32_e32 vcc, 0x800000, v117
	v_mul_f32_e32 v114, 0x4b800000, v117
	v_cndmask_b32_e32 v117, v117, v114, vcc
	v_rsq_f32_e32 v117, v117
	s_nop 0
	v_mul_f32_e32 v114, 0x45800000, v117
	v_cndmask_b32_e32 v117, v117, v114, vcc
	v_mul_f32_e32 v16, v16, v117
	v_mul_f32_e32 v16, v96, v16
	v_add_f32_e32 v64, 1.0, v64
	v_fma_f32 v16, v16, v64, v80
	v_mul_f32_e32 v17, v17, v117
	v_mul_f32_e32 v17, v97, v17
	v_add_f32_e32 v65, 1.0, v65
	v_fma_f32 v17, v17, v65, v81
	v_mul_f32_e32 v18, v18, v117
	v_mul_f32_e32 v18, v98, v18
	v_add_f32_e32 v66, 1.0, v66
	v_fma_f32 v18, v18, v66, v82
	v_mul_f32_e32 v19, v19, v117
	v_mul_f32_e32 v19, v99, v19
	v_add_f32_e32 v67, 1.0, v67
	v_fma_f32 v19, v19, v67, v83
	v_mul_f32_e32 v20, v20, v117
	v_mul_f32_e32 v20, v100, v20
	v_add_f32_e32 v68, 1.0, v68
	v_fma_f32 v20, v20, v68, v84
	v_mul_f32_e32 v21, v21, v117
	v_mul_f32_e32 v21, v101, v21
	v_add_f32_e32 v69, 1.0, v69
	v_fma_f32 v21, v21, v69, v85
	v_mul_f32_e32 v22, v22, v117
	v_mul_f32_e32 v22, v102, v22
	v_add_f32_e32 v70, 1.0, v70
	v_fma_f32 v22, v22, v70, v86
	v_mul_f32_e32 v23, v23, v117
	v_mul_f32_e32 v23, v103, v23
	v_add_f32_e32 v71, 1.0, v71
	v_fma_f32 v23, v23, v71, v87
	v_mul_f32_e32 v24, v24, v117
	v_mul_f32_e32 v24, v104, v24
	v_add_f32_e32 v72, 1.0, v72
	v_fma_f32 v24, v24, v72, v88
	v_mul_f32_e32 v25, v25, v117
	v_mul_f32_e32 v25, v105, v25
	v_add_f32_e32 v73, 1.0, v73
	v_fma_f32 v25, v25, v73, v89
	v_mul_f32_e32 v26, v26, v117
	v_mul_f32_e32 v26, v106, v26
	v_add_f32_e32 v74, 1.0, v74
	v_fma_f32 v26, v26, v74, v90
	v_mul_f32_e32 v27, v27, v117
	v_mul_f32_e32 v27, v107, v27
	v_add_f32_e32 v75, 1.0, v75
	v_fma_f32 v27, v27, v75, v91
	v_mul_f32_e32 v28, v28, v117
	v_mul_f32_e32 v28, v108, v28
	v_add_f32_e32 v76, 1.0, v76
	v_fma_f32 v28, v28, v76, v92
	v_mul_f32_e32 v29, v29, v117
	v_mul_f32_e32 v29, v109, v29
	v_add_f32_e32 v77, 1.0, v77
	v_fma_f32 v29, v29, v77, v93
	v_mul_f32_e32 v30, v30, v117
	v_mul_f32_e32 v30, v110, v30
	v_add_f32_e32 v78, 1.0, v78
	v_fma_f32 v30, v30, v78, v94
	v_mul_f32_e32 v31, v31, v117
	v_mul_f32_e32 v31, v111, v31
	v_add_f32_e32 v79, 1.0, v79
	v_fma_f32 v31, v31, v79, v95
	v_cvt_pk_bf16_f32 v16, v16, v17
	v_cvt_pk_bf16_f32 v17, v18, v19
	global_store_dwordx2 v116, v[16:17], s[10:11]
	v_cvt_pk_bf16_f32 v20, v20, v21
	v_cvt_pk_bf16_f32 v21, v22, v23
	global_store_dwordx2 v116, v[20:21], s[10:11] offset:512
	v_cvt_pk_bf16_f32 v24, v24, v25
	v_cvt_pk_bf16_f32 v25, v26, v27
	global_store_dwordx2 v116, v[24:25], s[10:11] offset:1024
	v_cvt_pk_bf16_f32 v28, v28, v29
	v_cvt_pk_bf16_f32 v29, v30, v31
	global_store_dwordx2 v116, v[28:29], s[10:11] offset:1536
	s_add_u32 s10, s10, 0x2000
	s_addc_u32 s11, s11, 0
	s_waitcnt vmcnt(0)
	s_branch .LBB0_807
